# lever 7 instruction selection: scan output-wave silu uses v_rcp_f32*g instead of the IEEE v_div_scale/fmas/fixup expansion (f32, about 1 ulp)
# speedup vs baseline: 1.0011x; 1.0011x over previous
.LBB0_270:
	s_and_b32 s17, s94, 1
	s_mul_i32 s23, s17, 0x4200
	s_waitcnt lgkmcnt(0)
	s_barrier
	v_add_u32_e32 v1, s23, v213
	s_waitcnt vmcnt(14) lgkmcnt(8)
	ds_read_b128 v[96:99], v1
	ds_read_b128 v[104:107], v1 offset:64
	ds_read_b128 v[100:103], v1 offset:8448
	ds_read_b128 v[108:111], v1 offset:8512
	s_add_i32 s23, s94, 2
	s_cmpk_lt_u32 s94, 0x7e
	s_waitcnt vmcnt(12) lgkmcnt(3)
	v_mfma_f32_16x16x32_bf16 v[96:99], v[96:99], v[64:67], 0
	s_cselect_b64 s[24:25], -1, 0
	s_and_b64 s[26:27], s[24:25], exec
	s_cselect_b32 s23, s23, 0x7f
	s_waitcnt lgkmcnt(1)
	v_mfma_f32_16x16x32_bf16 v[64:67], v[100:103], v[64:67], 0
	ds_read_b128 v[100:103], v1 offset:128
	s_lshl_b32 s26, s23, 6
	s_add_i32 s26, s26, s16
	s_waitcnt vmcnt(11)
	v_mfma_f32_16x16x32_bf16 v[96:99], v[104:107], v[56:59], v[96:99]
	ds_read_b128 v[104:107], v1 offset:8576
	s_mul_hi_i32 s27, s26, 0x6080
	s_mulk_i32 s26, 0x6080
	s_waitcnt lgkmcnt(2)
	v_mfma_f32_16x16x32_bf16 v[56:59], v[108:111], v[56:59], v[64:67]
	s_add_u32 s26, s56, s26
	s_addc_u32 s27, s57, s27
	v_lshl_add_u64 v[108:109], v[2:3], 1, s[26:27]
	ds_read_b128 v[64:67], v1 offset:192
	s_waitcnt vmcnt(10) lgkmcnt(2)
	v_mfma_f32_16x16x32_bf16 v[96:99], v[100:103], v[68:71], v[96:99]
	ds_read_b128 v[100:103], v1 offset:8640
	s_mul_i32 s74, s17, 0x1200
	v_add_u32_e32 v165, s74, v214
	s_waitcnt lgkmcnt(2)
	v_mfma_f32_16x16x32_bf16 v[56:59], v[104:107], v[68:71], v[56:59]
	v_add_co_u32_e32 v68, vcc, s81, v108
	s_add_i32 s23, s23, s93
	s_nop 0
	v_addc_co_u32_e32 v69, vcc, 0, v109, vcc
	global_load_dwordx4 v[136:139], v[108:109], off
	global_load_dwordx4 v[128:131], v[68:69], off offset:256
	ds_read_b128 v[68:71], v1 offset:256
	s_waitcnt vmcnt(11) lgkmcnt(2)
	v_mfma_f32_16x16x32_bf16 v[64:67], v[64:67], v[60:63], v[96:99]
	v_add_co_u32_e32 v104, vcc, s82, v108
	s_lshl_b32 s23, s23, 2
	s_waitcnt lgkmcnt(1)
	v_mfma_f32_16x16x32_bf16 v[56:59], v[100:103], v[60:63], v[56:59]
	ds_read_b128 v[60:63], v1 offset:8704
	ds_read_b128 v[96:99], v1 offset:320
	v_addc_co_u32_e32 v105, vcc, 0, v109, vcc
	v_add_co_u32_e32 v100, vcc, s83, v108
	s_waitcnt vmcnt(10) lgkmcnt(2)
	v_mfma_f32_16x16x32_bf16 v[64:67], v[68:71], v[80:83], v[64:67]
	v_addc_co_u32_e32 v101, vcc, 0, v109, vcc
	global_load_dwordx4 v[132:135], v[104:105], off offset:512
	global_load_dwordx4 v[120:123], v[100:101], off offset:768
	ds_read_b128 v[68:71], v1 offset:8768
	s_waitcnt lgkmcnt(2)
	v_mfma_f32_16x16x32_bf16 v[56:59], v[60:63], v[80:83], v[56:59]
	v_add_co_u32_e32 v80, vcc, s84, v108
	s_add_i32 s60, s23, s0
	s_waitcnt vmcnt(11) lgkmcnt(1)
	v_mfma_f32_16x16x32_bf16 v[60:63], v[96:99], v[72:75], v[64:67]
	v_addc_co_u32_e32 v81, vcc, 0, v109, vcc
	v_add_co_u32_e32 v82, vcc, s85, v108
	s_nop 0
	ds_read_b128 v[64:67], v1 offset:384
	v_addc_co_u32_e32 v83, vcc, 0, v109, vcc
	s_waitcnt lgkmcnt(1)
	v_mfma_f32_16x16x32_bf16 v[56:59], v[68:71], v[72:75], v[56:59]
	ds_read_b128 v[68:71], v1 offset:8832
	global_load_dwordx4 v[124:127], v[80:81], off offset:1024
	global_load_dwordx4 v[112:115], v[82:83], off offset:1280
	ds_read_b128 v[72:75], v1 offset:448
	s_waitcnt vmcnt(12) lgkmcnt(2)
	v_mfma_f32_16x16x32_bf16 v[60:63], v[64:67], v[88:91], v[60:63]
	ds_read_b128 v[64:67], v1 offset:8896
	v_add_co_u32_e32 v80, vcc, s89, v108
	s_waitcnt lgkmcnt(2)
	v_mfma_f32_16x16x32_bf16 v[56:59], v[68:71], v[88:91], v[56:59]
	v_addc_co_u32_e32 v81, vcc, 0, v109, vcc
	v_add_co_u32_e32 v82, vcc, s90, v108
	ds_read_b128 v[68:71], v165 offset:33792
	s_nop 0
	v_addc_co_u32_e32 v83, vcc, 0, v109, vcc
	s_waitcnt vmcnt(11) lgkmcnt(2)
	v_mfma_f32_16x16x32_bf16 v[60:63], v[72:75], v[84:87], v[60:63]
	global_load_dwordx4 v[116:119], v[80:81], off offset:1536
	global_load_dwordx4 v[108:111], v[82:83], off offset:1792
	ds_read_b128 v[72:75], v165 offset:36096
	s_ashr_i32 s61, s60, 31
	s_waitcnt lgkmcnt(2)
	v_mfma_f32_16x16x32_bf16 v[56:59], v[64:67], v[84:87], v[56:59]
	ds_read_b128 v[64:67], v165 offset:33856
	s_waitcnt vmcnt(9)
	v_lshlrev_b32_e32 v82, 16, v52
	v_and_b32_e32 v52, 0xffff0000, v52
	s_lshl_b64 s[60:61], s[60:61], 13
	s_waitcnt lgkmcnt(1)
	v_mfma_f32_16x16x32_bf16 v[56:59], v[72:75], v[92:95], v[56:59]
	v_mul_f32_e32 v72, 0xbfb8aa3b, v82
	v_mul_f32_e32 v73, 0xbfb8aa3b, v52
	v_lshl_add_u64 v[80:81], v[172:173], 0, s[60:61]
	v_mfma_f32_16x16x32_bf16 v[60:63], v[68:71], v[92:95], v[60:63]
	v_exp_f32_e32 v72, v72
	v_exp_f32_e32 v73, v73
	global_load_dwordx4 v[104:107], v[80:81], off
	global_load_dwordx4 v[100:103], v[80:81], off offset:1024
	ds_read_b128 v[68:71], v165 offset:36160
	s_waitcnt lgkmcnt(1)
	v_mfma_f32_16x16x32_bf16 v[60:63], v[64:67], v[76:79], v[60:63]
	v_add_f32_e64 v64, v72, 1.0
	v_add_f32_e64 v65, v73, 1.0
	v_lshl_add_u64 v[74:75], v[168:169], 1, s[26:27]
	v_lshl_add_u64 v[80:81], v[166:167], 1, s[26:27]
	s_waitcnt lgkmcnt(0)
	v_mfma_f32_16x16x32_bf16 v[56:59], v[68:71], v[76:79], v[56:59]
	v_and_b32_e32 v71, 0xffff0000, v53
	v_rcp_f32_e32 v66, v65
	s_nop 0
	v_mul_f32_e32 v65, v52, v66
	v_lshlrev_b32_e32 v69, 16, v53
	v_mul_f32_e32 v52, 0xbfb8aa3b, v69
	v_mul_f32_e32 v53, 0xbfb8aa3b, v71
	v_exp_f32_e32 v52, v52
	v_exp_f32_e32 v53, v53
	global_load_dwordx4 v[140:143], v[74:75], off
	global_load_dwordx4 v[96:99], v[80:81], off
	v_pk_add_f32 v[52:53], v[52:53], 1.0 op_sel_hi:[1,0]
	v_rcp_f32_e32 v66, v64
	s_nop 0
	v_mul_f32_e32 v64, v82, v66
	v_pk_mul_f32 v[64:65], v[64:65], v[60:61]
	v_lshl_add_u64 v[182:183], s[50:51], 0, v[178:179]
	v_cvt_pk_bf16_f32 v64, v64, v65
	v_rcp_f32_e32 v65, v53
	s_nop 0
	v_mul_f32_e32 v53, v71, v65
	v_lshlrev_b32_e32 v71, 16, v54
	v_and_b32_e32 v54, 0xffff0000, v54
	v_mul_f32_e32 v66, 0xbfb8aa3b, v71
	v_mul_f32_e32 v67, 0xbfb8aa3b, v54
	v_exp_f32_e32 v66, v66
	v_exp_f32_e32 v67, v67
	s_nop 0
	v_pk_add_f32 v[66:67], v[66:67], 1.0 op_sel_hi:[1,0]
	v_rcp_f32_e32 v65, v52
	s_nop 0
	v_mul_f32_e32 v52, v69, v65
	v_lshlrev_b32_e32 v72, 16, v55
	v_rcp_f32_e32 v65, v67
	s_nop 0
	v_mul_f32_e32 v67, v54, v65
	v_and_b32_e32 v73, 0xffff0000, v55
	v_mul_f32_e32 v54, 0xbfb8aa3b, v72
	v_mul_f32_e32 v55, 0xbfb8aa3b, v73
	v_exp_f32_e32 v54, v54
	v_exp_f32_e32 v55, v55
	s_nop 0
	v_pk_add_f32 v[54:55], v[54:55], 1.0 op_sel_hi:[1,0]
	v_rcp_f32_e32 v65, v66
	s_nop 0
	v_mul_f32_e32 v66, v71, v65
	v_pk_mul_f32 v[66:67], v[66:67], v[56:57]
	v_rcp_f32_e32 v65, v55
	s_nop 0
	v_mul_f32_e32 v55, v73, v65
	v_cvt_pk_bf16_f32 v66, v66, v67
	v_rcp_f32_e32 v65, v54
	s_nop 0
	v_mul_f32_e32 v54, v72, v65
	v_and_b32_e32 v68, 64, v228
	v_pk_mul_f32 v[54:55], v[54:55], v[58:59]
	v_xor_b32_e32 v65, 16, v228
	v_add_u32_e32 v70, 64, v68
	v_mov_b32_e32 v69, v56
	v_mov_b32_e32 v56, v61
	v_mov_b32_e32 v61, v58
	v_mov_b32_e32 v58, v63
	v_cmp_lt_i32_e32 vcc, v65, v70
	v_mov_b32_e32 v68, v60
	v_pk_mul_f32 v[56:57], v[56:57], v[56:57]
	v_mov_b32_e32 v60, v62
	v_pk_mul_f32 v[58:59], v[58:59], v[58:59]
	v_cndmask_b32_e32 v65, v228, v65, vcc
	v_pk_fma_f32 v[56:57], v[68:69], v[68:69], v[56:57]
	v_pk_fma_f32 v[58:59], v[60:61], v[60:61], v[58:59]
	v_lshlrev_b32_e32 v231, 2, v65
	v_pk_add_f32 v[56:57], v[56:57], v[58:59]
	ds_bpermute_b32 v58, v231, v56
	ds_bpermute_b32 v59, v231, v57
	v_cvt_pk_bf16_f32 v67, v54, v55
	v_xor_b32_e32 v54, 32, v228
	v_cmp_lt_i32_e32 vcc, v54, v70
	v_pk_mul_f32 v[52:53], v[52:53], v[62:63]
	s_mov_b32 s23, 0x7800000
	v_cndmask_b32_e32 v54, v228, v54, vcc
	v_cvt_pk_bf16_f32 v65, v52, v53
	s_waitcnt lgkmcnt(0)
	v_pk_add_f32 v[52:53], v[56:57], v[58:59]
	v_lshlrev_b32_e32 v232, 2, v54
	ds_bpermute_b32 v54, v232, v52
	ds_bpermute_b32 v55, v232, v53
	v_add_co_u32_e32 v56, vcc, s23, v182
	v_lshl_add_u64 v[180:181], s[50:51], 0, v[176:177]
	s_nop 0
	v_addc_co_u32_e32 v57, vcc, 0, v183, vcc
	global_store_dwordx4 v[56:57], v[64:67], off
	s_and_saveexec_b64 s[60:61], s[14:15]
	s_cbranch_execz .LBB0_272
	s_waitcnt lgkmcnt(0)
	v_pk_add_f32 v[52:53], v[52:53], v[54:55]
	v_add_co_u32_e32 v54, vcc, 0x4800000, v180
	s_nop 1
	v_addc_co_u32_e32 v55, vcc, 0, v181, vcc
	global_store_dwordx2 v[54:55], v[52:53], off
.LBB0_272:
	s_or_b64 exec, exec, s[60:61]
	s_xor_b32 s17, s17, 1
	s_mulk_i32 s17, 0x1200
	v_add_u32_e32 v233, s17, v212
	s_add_i32 s17, s94, 1
	s_and_b32 s17, s17, 1
	s_waitcnt vmcnt(14)
	ds_write_b16 v233, v44 offset:33792
	ds_write_b16_d16_hi v233, v44 offset:33936
	ds_write_b16 v233, v45 offset:34080
	ds_write_b16_d16_hi v233, v45 offset:34224
	ds_write_b16 v233, v46 offset:36096
	ds_write_b16_d16_hi v233, v46 offset:36240
	ds_write_b16 v233, v47 offset:36384
	ds_write_b16_d16_hi v233, v47 offset:36528
	s_mul_i32 s23, s17, 0x4200
	s_waitcnt lgkmcnt(0)
	s_barrier
	v_add_u32_e32 v146, s23, v213
	s_waitcnt lgkmcnt(8)
	ds_read_b128 v[52:55], v146
	ds_read_b128 v[60:63], v146 offset:64
	ds_read_b128 v[56:59], v146 offset:8448
	ds_read_b128 v[64:67], v146 offset:8512
	s_waitcnt lgkmcnt(3)
	v_mfma_f32_16x16x32_bf16 v[52:55], v[52:55], v[4:7], 0
	s_min_u32 s23, s94, 0x7c
	s_add_i32 s23, s23, 3
	s_lshl_b32 s26, s23, 6
	s_waitcnt lgkmcnt(2)
	v_mfma_f32_16x16x32_bf16 v[52:55], v[60:63], v[8:11], v[52:55]
	ds_read_b128 v[60:63], v146 offset:128
	ds_read_b128 v[76:79], v146 offset:192
	s_add_i32 s26, s26, s16
	s_mul_hi_i32 s27, s26, 0x6080
	s_mulk_i32 s26, 0x6080
	s_waitcnt lgkmcnt(3)
	v_mfma_f32_16x16x32_bf16 v[56:59], v[56:59], v[4:7], 0
	s_add_u32 s26, s56, s26
	s_addc_u32 s27, s57, s27
	ds_read_b128 v[72:75], v146 offset:8576
	v_lshl_add_u64 v[144:145], v[2:3], 1, s[26:27]
	s_waitcnt lgkmcnt(3)
	v_mfma_f32_16x16x32_bf16 v[68:71], v[64:67], v[8:11], v[56:59]
	s_add_i32 s23, s23, s93
	s_lshl_b32 s23, s23, 2
	s_add_i32 s60, s23, s0
	v_add_co_u32_e32 v56, vcc, s81, v144
	s_waitcnt lgkmcnt(2)
	v_mfma_f32_16x16x32_bf16 v[52:55], v[60:63], v[12:15], v[52:55]
	v_addc_co_u32_e32 v57, vcc, 0, v145, vcc
	global_load_dwordx4 v[64:67], v[144:145], off
	s_nop 0
	global_load_dwordx4 v[56:59], v[56:57], off offset:256
	ds_read_b128 v[60:63], v146 offset:8640
	s_waitcnt lgkmcnt(1)
	v_mfma_f32_16x16x32_bf16 v[68:71], v[72:75], v[12:15], v[68:71]
	v_add_co_u32_e32 v84, vcc, s82, v144
	ds_read_b128 v[72:75], v146 offset:256
	s_nop 0
	v_addc_co_u32_e32 v85, vcc, 0, v145, vcc
	v_add_co_u32_e32 v86, vcc, s83, v144
	v_mfma_f32_16x16x32_bf16 v[52:55], v[76:79], v[16:19], v[52:55]
	s_nop 0
	v_addc_co_u32_e32 v87, vcc, 0, v145, vcc
	ds_read_b128 v[80:83], v146 offset:8704
	s_waitcnt lgkmcnt(2)
	v_mfma_f32_16x16x32_bf16 v[76:79], v[60:63], v[16:19], v[68:71]
	s_nop 2
	global_load_dwordx4 v[68:71], v[84:85], off offset:512
	global_load_dwordx4 v[60:63], v[86:87], off offset:768
	ds_read_b128 v[84:87], v146 offset:320
	ds_read_b128 v[88:91], v146 offset:8768
	s_waitcnt lgkmcnt(3)
	v_mfma_f32_16x16x32_bf16 v[52:55], v[72:75], v[20:23], v[52:55]
	v_add_co_u32_e32 v72, vcc, s84, v144
	s_mul_i32 s23, s17, 0x1200
	s_waitcnt lgkmcnt(1)
	v_mfma_f32_16x16x32_bf16 v[52:55], v[84:87], v[24:27], v[52:55]
	ds_read_b128 v[84:87], v146 offset:384
	v_addc_co_u32_e32 v73, vcc, 0, v145, vcc
	v_mfma_f32_16x16x32_bf16 v[76:79], v[80:83], v[20:23], v[76:79]
	v_add_co_u32_e32 v74, vcc, s85, v144
	v_add_u32_e32 v242, s23, v214
	s_nop 0
	v_addc_co_u32_e32 v75, vcc, 0, v145, vcc
	global_load_dwordx4 v[80:83], v[72:73], off offset:1024
	s_nop 0
	global_load_dwordx4 v[72:75], v[74:75], off offset:1280
	s_waitcnt lgkmcnt(1)
	v_mfma_f32_16x16x32_bf16 v[76:79], v[88:91], v[24:27], v[76:79]
	ds_read_b128 v[88:91], v146 offset:8832
	ds_read_b128 v[92:95], v146 offset:448
	v_add_co_u32_e32 v234, vcc, s89, v144
	s_waitcnt lgkmcnt(2)
	v_mfma_f32_16x16x32_bf16 v[52:55], v[84:87], v[28:31], v[52:55]
	v_addc_co_u32_e32 v235, vcc, 0, v145, vcc
	v_add_co_u32_e32 v84, vcc, s90, v144
	s_waitcnt lgkmcnt(1)
	v_mfma_f32_16x16x32_bf16 v[76:79], v[88:91], v[28:31], v[76:79]
	v_addc_co_u32_e32 v85, vcc, 0, v145, vcc
	ds_read_b128 v[144:147], v146 offset:8896
	ds_read_b128 v[184:187], v242 offset:33792
	global_load_dwordx4 v[88:91], v[234:235], off offset:1536
	s_nop 0
	global_load_dwordx4 v[84:87], v[84:85], off offset:1792
	ds_read_b128 v[234:237], v242 offset:36096
	ds_read_b128 v[238:241], v242 offset:33856
	s_waitcnt lgkmcnt(3)
	v_mfma_f32_16x16x32_bf16 v[144:147], v[144:147], v[32:35], v[76:79]
	s_ashr_i32 s61, s60, 31
	s_waitcnt vmcnt(21)
	v_lshlrev_b32_e32 v246, 16, v48
	v_and_b32_e32 v247, 0xffff0000, v48
	v_mfma_f32_16x16x32_bf16 v[52:55], v[92:95], v[32:35], v[52:55]
	s_lshl_b64 s[60:61], s[60:61], 13
	v_lshl_add_u64 v[76:77], v[172:173], 0, s[60:61]
	global_load_dwordx4 v[92:95], v[76:77], off
	s_nop 0
	global_load_dwordx4 v[76:79], v[76:77], off offset:1024
	s_waitcnt lgkmcnt(1)
	v_mfma_f32_16x16x32_bf16 v[234:237], v[234:237], v[36:39], v[144:147]
	v_and_b32_e32 v251, 0xffff0000, v51
	s_mov_b32 s23, 0x7982000
	s_nop 0
	v_mul_f32_e32 v144, 0xbfb8aa3b, v246
	v_mul_f32_e32 v145, 0xbfb8aa3b, v247
	v_exp_f32_e32 v144, v144
	v_exp_f32_e32 v145, v145
	v_mfma_f32_16x16x32_bf16 v[52:55], v[184:187], v[36:39], v[52:55]
	ds_read_b128 v[184:187], v242 offset:36160
	v_lshl_add_u64 v[146:147], v[168:169], 1, s[26:27]
	v_pk_add_f32 v[244:245], v[144:145], 1.0 op_sel_hi:[1,0]
	v_lshl_add_u64 v[242:243], v[166:167], 1, s[26:27]
	s_waitcnt lgkmcnt(0)
	v_mfma_f32_16x16x32_bf16 v[184:187], v[184:187], v[40:43], v[234:237]
	s_nop 2
	s_nop 0
	v_mfma_f32_16x16x32_bf16 v[238:241], v[238:241], v[40:43], v[52:55]
	global_load_dwordx4 v[144:147], v[146:147], off
	s_nop 1
	s_nop 0
	global_load_dwordx4 v[52:55], v[242:243], off
	v_rcp_f32_e32 v234, v245
	s_nop 0
	v_mul_f32_e32 v235, v247, v234
	v_lshlrev_b32_e32 v247, 16, v49
	v_and_b32_e32 v248, 0xffff0000, v49
	v_mul_f32_e32 v236, 0xbfb8aa3b, v247
	v_mul_f32_e32 v237, 0xbfb8aa3b, v248
	v_exp_f32_e32 v236, v236
	v_exp_f32_e32 v237, v237
	v_rcp_f32_e32 v234, v244
	s_nop 0
	v_mul_f32_e32 v234, v246, v234
	v_pk_add_f32 v[236:237], v[236:237], 1.0 op_sel_hi:[1,0]
	v_pk_mul_f32 v[234:235], v[234:235], v[238:239]
	v_cvt_pk_bf16_f32 v234, v234, v235
	v_and_b32_e32 v249, 0xffff0000, v50
	v_rcp_f32_e32 v235, v237
	s_nop 0
	v_mul_f32_e32 v237, v248, v235
	v_lshlrev_b32_e32 v248, 16, v50
	v_mul_f32_e32 v242, 0xbfb8aa3b, v248
	v_mul_f32_e32 v243, 0xbfb8aa3b, v249
	v_exp_f32_e32 v242, v242
	v_exp_f32_e32 v243, v243
	s_nop 0
	v_pk_add_f32 v[242:243], v[242:243], 1.0 op_sel_hi:[1,0]
	v_rcp_f32_e32 v235, v236
	s_nop 0
	v_mul_f32_e32 v236, v247, v235
	v_pk_mul_f32 v[236:237], v[236:237], v[240:241]
	v_lshlrev_b32_e32 v250, 16, v51
	v_mul_f32_e32 v244, 0xbfb8aa3b, v250
	v_mul_f32_e32 v245, 0xbfb8aa3b, v251
	v_rcp_f32_e32 v235, v243
	s_nop 0
	v_mul_f32_e32 v243, v249, v235
	v_exp_f32_e32 v244, v244
	v_exp_f32_e32 v245, v245
	s_nop 0
	v_pk_add_f32 v[244:245], v[244:245], 1.0 op_sel_hi:[1,0]
	v_rcp_f32_e32 v235, v242
	s_nop 0
	v_mul_f32_e32 v242, v248, v235
	v_pk_mul_f32 v[242:243], v[242:243], v[184:185]
	v_rcp_f32_e32 v235, v245
	s_nop 0
	v_mul_f32_e32 v245, v251, v235
	v_rcp_f32_e32 v235, v244
	s_nop 0
	v_mul_f32_e32 v244, v250, v235
	v_pk_mul_f32 v[244:245], v[244:245], v[186:187]
	v_mov_b32_e32 v247, v184
	v_mov_b32_e32 v184, v239
	v_mov_b32_e32 v239, v186
	v_mov_b32_e32 v186, v241
	v_mov_b32_e32 v246, v238
	v_pk_mul_f32 v[184:185], v[184:185], v[184:185]
	v_mov_b32_e32 v238, v240
	v_pk_mul_f32 v[186:187], v[186:187], v[186:187]
	v_pk_fma_f32 v[184:185], v[246:247], v[246:247], v[184:185]
	v_pk_fma_f32 v[186:187], v[238:239], v[238:239], v[186:187]
	v_add_co_u32_e32 v182, vcc, s23, v182
	v_pk_add_f32 v[184:185], v[184:185], v[186:187]
	ds_bpermute_b32 v186, v231, v184
	ds_bpermute_b32 v187, v231, v185
	v_cvt_pk_bf16_f32 v235, v236, v237
	v_cvt_pk_bf16_f32 v236, v242, v243
	v_cvt_pk_bf16_f32 v237, v244, v245
	v_addc_co_u32_e32 v183, vcc, 0, v183, vcc
	s_waitcnt lgkmcnt(0)
	v_pk_add_f32 v[184:185], v[184:185], v[186:187]
	ds_bpermute_b32 v186, v232, v184
	ds_bpermute_b32 v187, v232, v185
	global_store_dwordx4 v[182:183], v[234:237], off
	s_and_saveexec_b64 s[60:61], s[14:15]
	s_cbranch_execz .LBB0_274
	v_add_co_u32_e32 v180, vcc, 0x4808000, v180
	s_waitcnt lgkmcnt(0)
	v_pk_add_f32 v[182:183], v[184:185], v[186:187]
	v_addc_co_u32_e32 v181, vcc, 0, v181, vcc
	global_store_dwordx2 v[180:181], v[182:183], off
.LBB0_274:
	s_or_b64 exec, exec, s[60:61]
	s_xor_b32 s17, s17, 1
	s_mulk_i32 s17, 0x1200
	v_add_u32_e32 v180, s17, v212
	s_andn2_b64 vcc, exec, s[24:25]
	s_waitcnt vmcnt(15)
	ds_write_b16 v180, v140 offset:33792
	ds_write_b16_d16_hi v180, v140 offset:33936
	ds_write_b16 v180, v141 offset:34080
	ds_write_b16_d16_hi v180, v141 offset:34224
	ds_write_b16 v180, v142 offset:36096
	ds_write_b16_d16_hi v180, v142 offset:36240
	ds_write_b16 v180, v143 offset:36384
	ds_write_b16_d16_hi v180, v143 offset:36528
	s_cbranch_vccnz .LBB0_269
	s_waitcnt lgkmcnt(0)
	s_barrier
	ds_read_b128 v[4:7], v1
	ds_read_b128 v[8:11], v1 offset:8448
	ds_read_b128 v[12:15], v1 offset:64
	ds_read_b128 v[20:23], v1 offset:128
	ds_read_b128 v[16:19], v1 offset:8512
	ds_read_b128 v[24:27], v1 offset:8640
	s_waitcnt lgkmcnt(5)
	v_mfma_f32_16x16x32_bf16 v[4:7], v[4:7], v[136:139], 0
	s_min_u32 s17, s94, 0x7b
	s_add_i32 s17, s17, 4
	s_lshl_b32 s23, s17, 6
	s_waitcnt lgkmcnt(4)
	v_mfma_f32_16x16x32_bf16 v[8:11], v[8:11], v[136:139], 0
	s_add_i32 s23, s23, s16
	s_mul_hi_i32 s25, s23, 0x6080
	s_mulk_i32 s23, 0x6080
	s_waitcnt lgkmcnt(3)
	v_mfma_f32_16x16x32_bf16 v[4:7], v[12:15], v[128:131], v[4:7]
	ds_read_b128 v[12:15], v1 offset:8576
	s_add_u32 s24, s56, s23
	s_addc_u32 s25, s57, s25
	s_waitcnt lgkmcnt(2)
	v_mfma_f32_16x16x32_bf16 v[8:11], v[16:19], v[128:131], v[8:11]
	ds_read_b128 v[16:19], v1 offset:192
	v_lshl_add_u64 v[128:129], v[2:3], 1, s[24:25]
	s_add_i32 s17, s17, s93
	v_mfma_f32_16x16x32_bf16 v[20:23], v[20:23], v[132:135], v[4:7]
	s_lshl_b32 s17, s17, 2
	s_add_i32 s26, s17, s0
	s_ashr_i32 s27, s26, 31
	s_waitcnt lgkmcnt(1)
	v_mfma_f32_16x16x32_bf16 v[12:15], v[12:15], v[132:135], v[8:11]
	s_lshl_b64 s[26:27], s[26:27], 13
	s_nop 1
	v_add_co_u32_e32 v8, vcc, s81, v128
	s_waitcnt lgkmcnt(0)
	v_mfma_f32_16x16x32_bf16 v[16:19], v[16:19], v[120:123], v[20:23]
	v_addc_co_u32_e32 v9, vcc, 0, v129, vcc
	global_load_dwordx4 v[4:7], v[128:129], off
	s_nop 0
	global_load_dwordx4 v[8:11], v[8:9], off offset:256
	ds_read_b128 v[20:23], v1 offset:256
	ds_read_b128 v[32:35], v1 offset:320
	v_add_co_u32_e32 v36, vcc, s82, v128
	ds_read_b128 v[28:31], v1 offset:8704
	s_nop 0
	v_addc_co_u32_e32 v37, vcc, 0, v129, vcc
	v_add_co_u32_e32 v38, vcc, s83, v128
	v_mfma_f32_16x16x32_bf16 v[24:27], v[24:27], v[120:123], v[12:15]
	s_nop 0
	v_addc_co_u32_e32 v39, vcc, 0, v129, vcc
	v_add_co_u32_e32 v44, vcc, s84, v128
	s_waitcnt lgkmcnt(2)
	v_mfma_f32_16x16x32_bf16 v[20:23], v[20:23], v[124:127], v[16:19]
	global_load_dwordx4 v[12:15], v[36:37], off offset:512
	s_nop 1
	global_load_dwordx4 v[16:19], v[38:39], off offset:768
	ds_read_b128 v[36:39], v1 offset:8768
	v_addc_co_u32_e32 v45, vcc, 0, v129, vcc
	s_waitcnt lgkmcnt(1)
	v_mfma_f32_16x16x32_bf16 v[24:27], v[28:31], v[124:127], v[24:27]
	v_add_co_u32_e32 v46, vcc, s85, v128
	ds_read_b128 v[40:43], v1 offset:8832
	v_mfma_f32_16x16x32_bf16 v[28:31], v[32:35], v[112:115], v[20:23]
	ds_read_b128 v[32:35], v1 offset:384
	v_addc_co_u32_e32 v47, vcc, 0, v129, vcc
	s_waitcnt lgkmcnt(2)
	v_mfma_f32_16x16x32_bf16 v[36:39], v[36:39], v[112:115], v[24:27]
	global_load_dwordx4 v[20:23], v[44:45], off offset:1024
	s_nop 1
	global_load_dwordx4 v[24:27], v[46:47], off offset:1280
	ds_read_b128 v[44:47], v1 offset:448
	ds_read_b128 v[48:51], v1 offset:8896
	s_waitcnt lgkmcnt(2)
	v_mfma_f32_16x16x32_bf16 v[28:31], v[32:35], v[116:119], v[28:31]
	v_add_co_u32_e32 v32, vcc, s89, v128
	s_waitcnt vmcnt(20)
	v_lshlrev_b32_e32 v1, 16, v96
	v_addc_co_u32_e32 v33, vcc, 0, v129, vcc
	v_add_co_u32_e32 v34, vcc, s90, v128
	v_mfma_f32_16x16x32_bf16 v[36:39], v[40:43], v[116:119], v[36:39]
	s_nop 0
	v_addc_co_u32_e32 v35, vcc, 0, v129, vcc
	ds_read_b128 v[40:43], v165 offset:33792
	s_waitcnt lgkmcnt(2)
	v_mfma_f32_16x16x32_bf16 v[44:47], v[44:47], v[108:111], v[28:31]
	s_nop 2
	global_load_dwordx4 v[28:31], v[32:33], off offset:1536
	s_nop 0
	global_load_dwordx4 v[32:35], v[34:35], off offset:1792
	ds_read_b128 v[112:115], v165 offset:36096
	v_and_b32_e32 v96, 0xffff0000, v96
	s_waitcnt lgkmcnt(2)
	v_mfma_f32_16x16x32_bf16 v[48:51], v[48:51], v[108:111], v[36:39]
	ds_read_b128 v[108:111], v165 offset:33856
	v_lshl_add_u64 v[116:117], v[172:173], 0, s[26:27]
	s_waitcnt lgkmcnt(2)
	v_mfma_f32_16x16x32_bf16 v[44:47], v[40:43], v[104:107], v[44:47]
	global_load_dwordx4 v[36:39], v[116:117], off
	global_load_dwordx4 v[40:43], v[116:117], off offset:1024
	ds_read_b128 v[116:119], v165 offset:36160
	s_waitcnt lgkmcnt(2)
	v_mfma_f32_16x16x32_bf16 v[104:107], v[112:115], v[104:107], v[48:51]
	v_lshl_add_u64 v[112:113], v[166:167], 1, s[24:25]
	s_nop 1
	v_mul_f32_e32 v48, 0xbfb8aa3b, v1
	v_mul_f32_e32 v49, 0xbfb8aa3b, v96
	v_exp_f32_e32 v48, v48
	v_exp_f32_e32 v49, v49
	v_lshl_add_u64 v[50:51], v[168:169], 1, s[24:25]
	s_waitcnt lgkmcnt(1)
	v_mfma_f32_16x16x32_bf16 v[108:111], v[108:111], v[100:103], v[44:47]
	v_add_f32_e64 v114, v48, 1.0
	v_add_f32_e64 v115, v49, 1.0
	s_waitcnt lgkmcnt(0)
	v_mfma_f32_16x16x32_bf16 v[100:103], v[116:119], v[100:103], v[104:107]
	global_load_dwordx4 v[44:47], v[50:51], off
	s_nop 0
	global_load_dwordx4 v[48:51], v[112:113], off
	v_and_b32_e32 v113, 0xffff0000, v97
	v_rcp_f32_e32 v104, v115
	s_nop 0
	v_mul_f32_e32 v105, v96, v104
	v_lshlrev_b32_e32 v115, 16, v97
	v_mul_f32_e32 v96, 0xbfb8aa3b, v115
	v_mul_f32_e32 v97, 0xbfb8aa3b, v113
	v_exp_f32_e32 v96, v96
	v_exp_f32_e32 v97, v97
	v_rcp_f32_e32 v104, v114
	s_nop 0
	v_mul_f32_e32 v104, v1, v104
	v_pk_add_f32 v[96:97], v[96:97], 1.0 op_sel_hi:[1,0]
	v_pk_mul_f32 v[104:105], v[104:105], v[108:109]
	v_cvt_pk_bf16_f32 v104, v104, v105
	v_and_b32_e32 v118, 0xffff0000, v99
	v_lshlrev_b32_e32 v105, 16, v98
	v_and_b32_e32 v98, 0xffff0000, v98
	v_mul_f32_e32 v106, 0xbfb8aa3b, v105
	v_mul_f32_e32 v107, 0xbfb8aa3b, v98
	v_exp_f32_e32 v106, v106
	v_exp_f32_e32 v107, v107
	v_rcp_f32_e32 v1, v97
	s_nop 0
	v_mul_f32_e32 v97, v113, v1
	v_pk_add_f32 v[106:107], v[106:107], 1.0 op_sel_hi:[1,0]
	v_rcp_f32_e32 v1, v96
	s_nop 0
	v_mul_f32_e32 v96, v115, v1
	v_rcp_f32_e32 v112, v107
	s_nop 0
	v_mul_f32_e32 v107, v98, v112
	v_lshlrev_b32_e32 v117, 16, v99
	v_mul_f32_e32 v98, 0xbfb8aa3b, v117
	v_mul_f32_e32 v99, 0xbfb8aa3b, v118
	v_exp_f32_e32 v98, v98
	v_exp_f32_e32 v99, v99
	s_nop 0
	v_pk_add_f32 v[98:99], v[98:99], 1.0 op_sel_hi:[1,0]
	v_rcp_f32_e32 v112, v106
	s_nop 0
	v_mul_f32_e32 v106, v105, v112
	v_pk_mul_f32 v[106:107], v[106:107], v[100:101]
	v_rcp_f32_e32 v105, v99
	s_nop 0
	v_mul_f32_e32 v99, v118, v105
	v_pk_mul_f32 v[96:97], v[96:97], v[110:111]
	v_rcp_f32_e32 v105, v98
	s_nop 0
	v_mul_f32_e32 v98, v117, v105
	v_pk_mul_f32 v[112:113], v[98:99], v[102:103]
	v_mov_b32_e32 v99, v100
	v_mov_b32_e32 v100, v109
	v_mov_b32_e32 v98, v108
	v_pk_mul_f32 v[100:101], v[100:101], v[100:101]
	v_cvt_pk_bf16_f32 v105, v96, v97
	v_pk_fma_f32 v[98:99], v[98:99], v[98:99], v[100:101]
	v_mov_b32_e32 v101, v102
	v_mov_b32_e32 v102, v111
	v_mov_b32_e32 v100, v110
	v_pk_mul_f32 v[102:103], v[102:103], v[102:103]
	v_cvt_pk_bf16_f32 v106, v106, v107
	v_pk_fma_f32 v[100:101], v[100:101], v[100:101], v[102:103]
	v_cvt_pk_bf16_f32 v107, v112, v113
	v_pk_add_f32 v[98:99], v[98:99], v[100:101]
	ds_bpermute_b32 v100, v231, v98
	ds_bpermute_b32 v101, v231, v99
	s_waitcnt lgkmcnt(0)
	v_pk_add_f32 v[96:97], v[98:99], v[100:101]
	ds_bpermute_b32 v98, v232, v96
	ds_bpermute_b32 v99, v232, v97
	v_mad_i64_i32 v[100:101], s[24:25], s22, v230, v[170:171]
	global_store_dwordx4 v[100:101], v[104:107], off
	s_and_saveexec_b64 s[24:25], s[14:15]
	s_cbranch_execz .LBB0_268
	s_ashr_i32 s23, s22, 31
	s_lshl_b64 s[26:27], s[22:23], 9
	v_lshl_add_u64 v[100:101], v[174:175], 0, s[26:27]
	s_waitcnt lgkmcnt(0)
	v_pk_add_f32 v[96:97], v[96:97], v[98:99]
	global_store_dwordx2 v[100:101], v[96:97], off
	s_branch .LBB0_268

.LBB0_712:
	s_and_b32 s7, s37, 1
	s_mul_i32 s11, s7, 0x4200
	s_waitcnt lgkmcnt(0)
	s_barrier
	v_add_u32_e32 v196, s11, v185
	s_waitcnt vmcnt(14) lgkmcnt(8)
	ds_read_b128 v[94:97], v196
	ds_read_b128 v[102:105], v196 offset:64
	ds_read_b128 v[98:101], v196 offset:8448
	ds_read_b128 v[106:109], v196 offset:8512
	s_add_i32 s11, s37, 2
	s_cmpk_lt_u32 s37, 0x7e
	s_waitcnt vmcnt(12) lgkmcnt(3)
	v_mfma_f32_16x16x32_bf16 v[94:97], v[94:97], v[62:65], 0
	s_cselect_b64 s[12:13], -1, 0
	s_and_b64 s[14:15], s[12:13], exec
	s_cselect_b32 s11, s11, 0x7f
	s_waitcnt lgkmcnt(1)
	v_mfma_f32_16x16x32_bf16 v[62:65], v[98:101], v[62:65], 0
	ds_read_b128 v[98:101], v196 offset:128
	s_lshl_b32 s14, s11, 6
	s_add_i32 s14, s14, s6
	s_waitcnt vmcnt(11)
	v_mfma_f32_16x16x32_bf16 v[94:97], v[102:105], v[54:57], v[94:97]
	ds_read_b128 v[102:105], v196 offset:8576
	s_mul_hi_i32 s15, s14, 0x6080
	s_mulk_i32 s14, 0x6080
	s_waitcnt lgkmcnt(2)
	v_mfma_f32_16x16x32_bf16 v[54:57], v[106:109], v[54:57], v[62:65]
	s_add_u32 s14, s56, s14
	s_addc_u32 s15, s57, s15
	v_lshl_add_u64 v[106:107], v[0:1], 1, s[14:15]
	ds_read_b128 v[62:65], v196 offset:192
	s_waitcnt vmcnt(10) lgkmcnt(2)
	v_mfma_f32_16x16x32_bf16 v[94:97], v[98:101], v[66:69], v[94:97]
	ds_read_b128 v[98:101], v196 offset:8640
	s_mul_i32 s40, s7, 0x1200
	v_add_u32_e32 v197, s40, v186
	s_waitcnt lgkmcnt(2)
	v_mfma_f32_16x16x32_bf16 v[54:57], v[102:105], v[66:69], v[54:57]
	v_add_co_u32_e32 v66, vcc, s18, v106
	s_add_i32 s11, s11, s36
	s_nop 0
	v_addc_co_u32_e32 v67, vcc, 0, v107, vcc
	global_load_dwordx4 v[134:137], v[106:107], off
	global_load_dwordx4 v[126:129], v[66:67], off offset:256
	ds_read_b128 v[66:69], v196 offset:256
	s_waitcnt vmcnt(11) lgkmcnt(2)
	v_mfma_f32_16x16x32_bf16 v[62:65], v[62:65], v[58:61], v[94:97]
	v_add_co_u32_e32 v102, vcc, s19, v106
	s_lshl_b32 s11, s11, 3
	s_waitcnt lgkmcnt(1)
	v_mfma_f32_16x16x32_bf16 v[54:57], v[98:101], v[58:61], v[54:57]
	ds_read_b128 v[58:61], v196 offset:8704
	ds_read_b128 v[94:97], v196 offset:320
	v_addc_co_u32_e32 v103, vcc, 0, v107, vcc
	v_add_co_u32_e32 v98, vcc, s20, v106
	s_waitcnt vmcnt(10) lgkmcnt(2)
	v_mfma_f32_16x16x32_bf16 v[62:65], v[66:69], v[78:81], v[62:65]
	v_addc_co_u32_e32 v99, vcc, 0, v107, vcc
	global_load_dwordx4 v[130:133], v[102:103], off offset:512
	global_load_dwordx4 v[118:121], v[98:99], off offset:768
	ds_read_b128 v[66:69], v196 offset:8768
	s_waitcnt lgkmcnt(2)
	v_mfma_f32_16x16x32_bf16 v[54:57], v[58:61], v[78:81], v[54:57]
	v_add_co_u32_e32 v78, vcc, s21, v106
	s_add_i32 s38, s11, s35
	s_waitcnt vmcnt(11) lgkmcnt(1)
	v_mfma_f32_16x16x32_bf16 v[58:61], v[94:97], v[70:73], v[62:65]
	v_addc_co_u32_e32 v79, vcc, 0, v107, vcc
	v_add_co_u32_e32 v80, vcc, s22, v106
	s_nop 0
	ds_read_b128 v[62:65], v196 offset:384
	v_addc_co_u32_e32 v81, vcc, 0, v107, vcc
	s_waitcnt lgkmcnt(1)
	v_mfma_f32_16x16x32_bf16 v[54:57], v[66:69], v[70:73], v[54:57]
	ds_read_b128 v[66:69], v196 offset:8832
	global_load_dwordx4 v[122:125], v[78:79], off offset:1024
	global_load_dwordx4 v[110:113], v[80:81], off offset:1280
	ds_read_b128 v[70:73], v196 offset:448
	s_waitcnt vmcnt(12) lgkmcnt(2)
	v_mfma_f32_16x16x32_bf16 v[58:61], v[62:65], v[86:89], v[58:61]
	ds_read_b128 v[62:65], v196 offset:8896
	v_add_co_u32_e32 v78, vcc, s23, v106
	s_waitcnt lgkmcnt(2)
	v_mfma_f32_16x16x32_bf16 v[54:57], v[66:69], v[86:89], v[54:57]
	v_addc_co_u32_e32 v79, vcc, 0, v107, vcc
	v_add_co_u32_e32 v80, vcc, s24, v106
	ds_read_b128 v[66:69], v197 offset:33792
	s_nop 0
	v_addc_co_u32_e32 v81, vcc, 0, v107, vcc
	s_waitcnt vmcnt(11) lgkmcnt(2)
	v_mfma_f32_16x16x32_bf16 v[58:61], v[70:73], v[82:85], v[58:61]
	global_load_dwordx4 v[114:117], v[78:79], off offset:1536
	global_load_dwordx4 v[106:109], v[80:81], off offset:1792
	ds_read_b128 v[70:73], v197 offset:36096
	s_ashr_i32 s39, s38, 31
	s_waitcnt lgkmcnt(2)
	v_mfma_f32_16x16x32_bf16 v[54:57], v[62:65], v[82:85], v[54:57]
	ds_read_b128 v[62:65], v197 offset:33856
	s_waitcnt vmcnt(9)
	v_lshlrev_b32_e32 v80, 16, v50
	v_and_b32_e32 v50, 0xffff0000, v50
	s_lshl_b64 s[38:39], s[38:39], 13
	s_waitcnt lgkmcnt(1)
	v_mfma_f32_16x16x32_bf16 v[54:57], v[70:73], v[90:93], v[54:57]
	v_mul_f32_e32 v70, 0xbfb8aa3b, v80
	v_mul_f32_e32 v71, 0xbfb8aa3b, v50
	v_lshl_add_u64 v[78:79], v[154:155], 0, s[38:39]
	v_mfma_f32_16x16x32_bf16 v[58:61], v[66:69], v[90:93], v[58:61]
	v_exp_f32_e32 v70, v70
	v_exp_f32_e32 v71, v71
	global_load_dwordx4 v[102:105], v[78:79], off
	global_load_dwordx4 v[98:101], v[78:79], off offset:1024
	ds_read_b128 v[66:69], v197 offset:36160
	s_waitcnt lgkmcnt(1)
	v_mfma_f32_16x16x32_bf16 v[58:61], v[62:65], v[74:77], v[58:61]
	v_add_f32_e64 v62, v70, 1.0
	v_add_f32_e64 v63, v71, 1.0
	v_lshl_add_u64 v[72:73], v[150:151], 1, s[14:15]
	v_lshl_add_u64 v[78:79], v[148:149], 1, s[14:15]
	s_waitcnt lgkmcnt(0)
	v_mfma_f32_16x16x32_bf16 v[54:57], v[66:69], v[74:77], v[54:57]
	v_and_b32_e32 v69, 0xffff0000, v51
	v_rcp_f32_e32 v64, v63
	s_nop 0
	v_mul_f32_e32 v63, v50, v64
	v_lshlrev_b32_e32 v67, 16, v51
	v_mul_f32_e32 v50, 0xbfb8aa3b, v67
	v_mul_f32_e32 v51, 0xbfb8aa3b, v69
	v_exp_f32_e32 v50, v50
	v_exp_f32_e32 v51, v51
	global_load_dwordx4 v[138:141], v[72:73], off
	global_load_dwordx4 v[94:97], v[78:79], off
	v_pk_add_f32 v[50:51], v[50:51], 1.0 op_sel_hi:[1,0]
	v_rcp_f32_e32 v64, v62
	s_nop 0
	v_mul_f32_e32 v62, v80, v64
	v_pk_mul_f32 v[62:63], v[62:63], v[58:59]
	v_lshl_add_u64 v[164:165], s[50:51], 0, v[160:161]
	v_cvt_pk_bf16_f32 v62, v62, v63
	v_rcp_f32_e32 v63, v51
	s_nop 0
	v_mul_f32_e32 v51, v69, v63
	v_lshlrev_b32_e32 v69, 16, v52
	v_and_b32_e32 v52, 0xffff0000, v52
	v_mul_f32_e32 v64, 0xbfb8aa3b, v69
	v_mul_f32_e32 v65, 0xbfb8aa3b, v52
	v_exp_f32_e32 v64, v64
	v_exp_f32_e32 v65, v65
	s_nop 0
	v_pk_add_f32 v[64:65], v[64:65], 1.0 op_sel_hi:[1,0]
	v_rcp_f32_e32 v63, v50
	s_nop 0
	v_mul_f32_e32 v50, v67, v63
	v_lshlrev_b32_e32 v70, 16, v53
	v_rcp_f32_e32 v63, v65
	s_nop 0
	v_mul_f32_e32 v65, v52, v63
	v_and_b32_e32 v71, 0xffff0000, v53
	v_mul_f32_e32 v52, 0xbfb8aa3b, v70
	v_mul_f32_e32 v53, 0xbfb8aa3b, v71
	v_exp_f32_e32 v52, v52
	v_exp_f32_e32 v53, v53
	s_nop 0
	v_pk_add_f32 v[52:53], v[52:53], 1.0 op_sel_hi:[1,0]
	v_rcp_f32_e32 v63, v64
	s_nop 0
	v_mul_f32_e32 v64, v69, v63
	v_pk_mul_f32 v[64:65], v[64:65], v[54:55]
	v_rcp_f32_e32 v63, v53
	s_nop 0
	v_mul_f32_e32 v53, v71, v63
	v_cvt_pk_bf16_f32 v64, v64, v65
	v_rcp_f32_e32 v63, v52
	s_nop 0
	v_mul_f32_e32 v52, v70, v63
	v_and_b32_e32 v66, 64, v195
	v_pk_mul_f32 v[52:53], v[52:53], v[56:57]
	v_xor_b32_e32 v63, 16, v195
	v_add_u32_e32 v68, 64, v66
	v_mov_b32_e32 v67, v54
	v_mov_b32_e32 v54, v59
	v_mov_b32_e32 v59, v56
	v_mov_b32_e32 v56, v61
	v_cmp_lt_i32_e32 vcc, v63, v68
	v_mov_b32_e32 v66, v58
	v_pk_mul_f32 v[54:55], v[54:55], v[54:55]
	v_mov_b32_e32 v58, v60
	v_pk_mul_f32 v[56:57], v[56:57], v[56:57]
	v_cndmask_b32_e32 v63, v195, v63, vcc
	v_pk_fma_f32 v[54:55], v[66:67], v[66:67], v[54:55]
	v_pk_fma_f32 v[56:57], v[58:59], v[58:59], v[56:57]
	v_lshlrev_b32_e32 v198, 2, v63
	v_pk_add_f32 v[54:55], v[54:55], v[56:57]
	ds_bpermute_b32 v56, v198, v54
	ds_bpermute_b32 v57, v198, v55
	v_cvt_pk_bf16_f32 v65, v52, v53
	v_xor_b32_e32 v52, 32, v195
	v_cmp_lt_i32_e32 vcc, v52, v68
	v_pk_mul_f32 v[50:51], v[50:51], v[60:61]
	v_lshl_add_u64 v[162:163], s[50:51], 0, v[158:159]
	v_cndmask_b32_e32 v52, v195, v52, vcc
	v_cvt_pk_bf16_f32 v63, v50, v51
	s_waitcnt lgkmcnt(0)
	v_pk_add_f32 v[50:51], v[54:55], v[56:57]
	v_lshlrev_b32_e32 v200, 2, v52
	ds_bpermute_b32 v52, v200, v50
	ds_bpermute_b32 v53, v200, v51
	v_add_co_u32_e32 v54, vcc, s25, v164
	s_nop 1
	v_addc_co_u32_e32 v55, vcc, 0, v165, vcc
	global_store_dwordx4 v[54:55], v[62:65], off
	s_and_saveexec_b64 s[14:15], s[4:5]
	s_cbranch_execz .LBB0_714
	s_waitcnt lgkmcnt(0)
	v_pk_add_f32 v[50:51], v[50:51], v[52:53]
	v_add_co_u32_e32 v52, vcc, 0x4800000, v162
	s_nop 1
	v_addc_co_u32_e32 v53, vcc, 0, v163, vcc
	global_store_dwordx2 v[52:53], v[50:51], off
.LBB0_714:
	s_or_b64 exec, exec, s[14:15]
	s_xor_b32 s7, s7, 1
	s_mulk_i32 s7, 0x1200
	v_add_u32_e32 v199, s7, v184
	s_add_i32 s7, s37, 1
	s_and_b32 s7, s7, 1
	s_waitcnt vmcnt(14)
	ds_write_b16 v199, v42 offset:33792
	ds_write_b16_d16_hi v199, v42 offset:33936
	ds_write_b16 v199, v43 offset:34080
	ds_write_b16_d16_hi v199, v43 offset:34224
	ds_write_b16 v199, v44 offset:36096
	ds_write_b16_d16_hi v199, v44 offset:36240
	ds_write_b16 v199, v45 offset:36384
	ds_write_b16_d16_hi v199, v45 offset:36528
	s_mul_i32 s11, s7, 0x4200
	s_waitcnt lgkmcnt(0)
	s_barrier
	v_add_u32_e32 v144, s11, v185
	s_waitcnt lgkmcnt(8)
	ds_read_b128 v[50:53], v144
	ds_read_b128 v[58:61], v144 offset:64
	ds_read_b128 v[54:57], v144 offset:8448
	ds_read_b128 v[62:65], v144 offset:8512
	s_waitcnt lgkmcnt(3)
	v_mfma_f32_16x16x32_bf16 v[50:53], v[50:53], v[2:5], 0
	s_min_u32 s11, s37, 0x7c
	s_add_i32 s11, s11, 3
	s_lshl_b32 s14, s11, 6
	s_waitcnt lgkmcnt(2)
	v_mfma_f32_16x16x32_bf16 v[50:53], v[58:61], v[6:9], v[50:53]
	ds_read_b128 v[58:61], v144 offset:128
	ds_read_b128 v[74:77], v144 offset:192
	s_add_i32 s14, s14, s6
	s_mul_hi_i32 s15, s14, 0x6080
	s_mulk_i32 s14, 0x6080
	s_waitcnt lgkmcnt(3)
	v_mfma_f32_16x16x32_bf16 v[54:57], v[54:57], v[2:5], 0
	s_add_u32 s14, s56, s14
	s_addc_u32 s15, s57, s15
	ds_read_b128 v[70:73], v144 offset:8576
	v_lshl_add_u64 v[142:143], v[0:1], 1, s[14:15]
	s_waitcnt lgkmcnt(3)
	v_mfma_f32_16x16x32_bf16 v[66:69], v[62:65], v[6:9], v[54:57]
	s_add_i32 s11, s11, s36
	s_lshl_b32 s11, s11, 3
	s_add_i32 s38, s11, s35
	v_add_co_u32_e32 v54, vcc, s18, v142
	s_waitcnt lgkmcnt(2)
	v_mfma_f32_16x16x32_bf16 v[50:53], v[58:61], v[10:13], v[50:53]
	v_addc_co_u32_e32 v55, vcc, 0, v143, vcc
	global_load_dwordx4 v[62:65], v[142:143], off
	s_nop 0
	global_load_dwordx4 v[54:57], v[54:55], off offset:256
	ds_read_b128 v[58:61], v144 offset:8640
	s_waitcnt lgkmcnt(1)
	v_mfma_f32_16x16x32_bf16 v[66:69], v[70:73], v[10:13], v[66:69]
	v_add_co_u32_e32 v82, vcc, s19, v142
	ds_read_b128 v[70:73], v144 offset:256
	s_nop 0
	v_addc_co_u32_e32 v83, vcc, 0, v143, vcc
	v_add_co_u32_e32 v84, vcc, s20, v142
	v_mfma_f32_16x16x32_bf16 v[50:53], v[74:77], v[14:17], v[50:53]
	s_nop 0
	v_addc_co_u32_e32 v85, vcc, 0, v143, vcc
	ds_read_b128 v[78:81], v144 offset:8704
	s_waitcnt lgkmcnt(2)
	v_mfma_f32_16x16x32_bf16 v[74:77], v[58:61], v[14:17], v[66:69]
	s_nop 2
	global_load_dwordx4 v[66:69], v[82:83], off offset:512
	global_load_dwordx4 v[58:61], v[84:85], off offset:768
	ds_read_b128 v[82:85], v144 offset:320
	ds_read_b128 v[86:89], v144 offset:8768
	s_waitcnt lgkmcnt(3)
	v_mfma_f32_16x16x32_bf16 v[50:53], v[70:73], v[18:21], v[50:53]
	v_add_co_u32_e32 v70, vcc, s21, v142
	s_mul_i32 s11, s7, 0x1200
	s_waitcnt lgkmcnt(1)
	v_mfma_f32_16x16x32_bf16 v[50:53], v[82:85], v[22:25], v[50:53]
	ds_read_b128 v[82:85], v144 offset:384
	v_addc_co_u32_e32 v71, vcc, 0, v143, vcc
	v_mfma_f32_16x16x32_bf16 v[74:77], v[78:81], v[18:21], v[74:77]
	v_add_co_u32_e32 v72, vcc, s22, v142
	v_add_u32_e32 v201, s11, v186
	s_nop 0
	v_addc_co_u32_e32 v73, vcc, 0, v143, vcc
	global_load_dwordx4 v[78:81], v[70:71], off offset:1024
	s_nop 0
	global_load_dwordx4 v[70:73], v[72:73], off offset:1280
	s_waitcnt lgkmcnt(1)
	v_mfma_f32_16x16x32_bf16 v[74:77], v[86:89], v[22:25], v[74:77]
	ds_read_b128 v[86:89], v144 offset:8832
	ds_read_b128 v[90:93], v144 offset:448
	v_add_co_u32_e32 v202, vcc, s23, v142
	s_waitcnt lgkmcnt(2)
	v_mfma_f32_16x16x32_bf16 v[50:53], v[82:85], v[26:29], v[50:53]
	v_addc_co_u32_e32 v203, vcc, 0, v143, vcc
	v_add_co_u32_e32 v82, vcc, s24, v142
	ds_read_b128 v[166:169], v201 offset:33792
	s_nop 0
	v_addc_co_u32_e32 v83, vcc, 0, v143, vcc
	ds_read_b128 v[142:145], v144 offset:8896
	s_waitcnt lgkmcnt(3)
	v_mfma_f32_16x16x32_bf16 v[74:77], v[86:89], v[26:29], v[74:77]
	global_load_dwordx4 v[86:89], v[202:203], off offset:1536
	s_nop 0
	global_load_dwordx4 v[82:85], v[82:83], off offset:1792
	ds_read_b128 v[202:205], v201 offset:36096
	ds_read_b128 v[206:209], v201 offset:33856
	s_waitcnt lgkmcnt(4)
	v_mfma_f32_16x16x32_bf16 v[50:53], v[90:93], v[30:33], v[50:53]
	s_ashr_i32 s39, s38, 31
	s_lshl_b64 s[38:39], s[38:39], 13
	s_waitcnt vmcnt(21)
	v_and_b32_e32 v214, 0xffff0000, v46
	s_waitcnt lgkmcnt(2)
	v_mfma_f32_16x16x32_bf16 v[142:145], v[142:145], v[30:33], v[74:77]
	v_lshl_add_u64 v[210:211], v[148:149], 1, s[14:15]
	s_nop 1
	v_lshl_add_u64 v[74:75], v[154:155], 0, s[38:39]
	v_mfma_f32_16x16x32_bf16 v[50:53], v[166:169], v[34:37], v[50:53]
	global_load_dwordx4 v[90:93], v[74:75], off
	s_nop 0
	global_load_dwordx4 v[74:77], v[74:75], off offset:1024
	ds_read_b128 v[166:169], v201 offset:36160
	v_lshlrev_b32_e32 v201, 16, v46
	s_waitcnt lgkmcnt(2)
	v_mfma_f32_16x16x32_bf16 v[202:205], v[202:205], v[34:37], v[142:145]
	s_nop 2
	v_mul_f32_e32 v142, 0xbfb8aa3b, v201
	v_mul_f32_e32 v143, 0xbfb8aa3b, v214
	v_exp_f32_e32 v142, v142
	v_exp_f32_e32 v143, v143
	v_lshl_add_u64 v[144:145], v[150:151], 1, s[14:15]
	s_waitcnt lgkmcnt(0)
	v_mfma_f32_16x16x32_bf16 v[166:169], v[166:169], v[38:41], v[202:205]
	v_add_f32_e64 v212, v142, 1.0
	v_add_f32_e64 v213, v143, 1.0
	v_mfma_f32_16x16x32_bf16 v[206:209], v[206:209], v[38:41], v[50:53]
	global_load_dwordx4 v[142:145], v[144:145], off
	s_nop 1
	s_nop 0
	global_load_dwordx4 v[50:53], v[210:211], off
	v_rcp_f32_e32 v202, v213
	s_nop 0
	v_mul_f32_e32 v203, v214, v202
	v_lshlrev_b32_e32 v214, 16, v47
	v_and_b32_e32 v215, 0xffff0000, v47
	v_mul_f32_e32 v204, 0xbfb8aa3b, v214
	v_mul_f32_e32 v205, 0xbfb8aa3b, v215
	v_exp_f32_e32 v204, v204
	v_exp_f32_e32 v205, v205
	v_rcp_f32_e32 v202, v212
	s_nop 0
	v_mul_f32_e32 v202, v201, v202
	v_pk_add_f32 v[204:205], v[204:205], 1.0 op_sel_hi:[1,0]
	v_pk_mul_f32 v[202:203], v[202:203], v[206:207]
	v_cvt_pk_bf16_f32 v202, v202, v203
	v_and_b32_e32 v216, 0xffff0000, v48
	v_rcp_f32_e32 v201, v205
	s_nop 0
	v_mul_f32_e32 v205, v215, v201
	v_lshlrev_b32_e32 v215, 16, v48
	v_mul_f32_e32 v210, 0xbfb8aa3b, v215
	v_mul_f32_e32 v211, 0xbfb8aa3b, v216
	v_exp_f32_e32 v210, v210
	v_exp_f32_e32 v211, v211
	s_nop 0
	v_pk_add_f32 v[210:211], v[210:211], 1.0 op_sel_hi:[1,0]
	v_rcp_f32_e32 v201, v204
	s_nop 0
	v_mul_f32_e32 v204, v214, v201
	v_rcp_f32_e32 v201, v211
	s_nop 0
	v_mul_f32_e32 v211, v216, v201
	v_lshlrev_b32_e32 v216, 16, v49
	v_and_b32_e32 v217, 0xffff0000, v49
	v_mul_f32_e32 v212, 0xbfb8aa3b, v216
	v_mul_f32_e32 v213, 0xbfb8aa3b, v217
	v_exp_f32_e32 v212, v212
	v_exp_f32_e32 v213, v213
	s_nop 0
	v_pk_add_f32 v[212:213], v[212:213], 1.0 op_sel_hi:[1,0]
	v_rcp_f32_e32 v201, v210
	s_nop 0
	v_mul_f32_e32 v210, v215, v201
	v_pk_mul_f32 v[210:211], v[210:211], v[166:167]
	v_rcp_f32_e32 v201, v213
	s_nop 0
	v_mul_f32_e32 v213, v217, v201
	v_pk_mul_f32 v[204:205], v[204:205], v[208:209]
	v_rcp_f32_e32 v201, v212
	s_nop 0
	v_mul_f32_e32 v212, v216, v201
	v_pk_mul_f32 v[212:213], v[212:213], v[168:169]
	v_mov_b32_e32 v215, v166
	v_mov_b32_e32 v166, v207
	v_mov_b32_e32 v207, v168
	v_mov_b32_e32 v168, v209
	v_mov_b32_e32 v214, v206
	v_pk_mul_f32 v[166:167], v[166:167], v[166:167]
	v_mov_b32_e32 v206, v208
	v_pk_mul_f32 v[168:169], v[168:169], v[168:169]
	v_pk_fma_f32 v[166:167], v[214:215], v[214:215], v[166:167]
	v_pk_fma_f32 v[168:169], v[206:207], v[206:207], v[168:169]
	v_add_co_u32_e32 v164, vcc, s26, v164
	v_pk_add_f32 v[166:167], v[166:167], v[168:169]
	ds_bpermute_b32 v168, v198, v166
	ds_bpermute_b32 v169, v198, v167
	v_cvt_pk_bf16_f32 v203, v204, v205
	v_cvt_pk_bf16_f32 v204, v210, v211
	v_cvt_pk_bf16_f32 v205, v212, v213
	v_addc_co_u32_e32 v165, vcc, 0, v165, vcc
	s_waitcnt lgkmcnt(0)
	v_pk_add_f32 v[166:167], v[166:167], v[168:169]
	ds_bpermute_b32 v168, v200, v166
	ds_bpermute_b32 v169, v200, v167
	global_store_dwordx4 v[164:165], v[202:205], off
	s_and_saveexec_b64 s[14:15], s[4:5]
	s_cbranch_execz .LBB0_716
	v_add_co_u32_e32 v162, vcc, 0x4810000, v162
	s_waitcnt lgkmcnt(0)
	v_pk_add_f32 v[164:165], v[166:167], v[168:169]
	v_addc_co_u32_e32 v163, vcc, 0, v163, vcc
	global_store_dwordx2 v[162:163], v[164:165], off
.LBB0_716:
	s_or_b64 exec, exec, s[14:15]
	s_xor_b32 s7, s7, 1
	s_mulk_i32 s7, 0x1200
	v_add_u32_e32 v162, s7, v184
	s_andn2_b64 vcc, exec, s[12:13]
	s_waitcnt vmcnt(15)
	ds_write_b16 v162, v138 offset:33792
	ds_write_b16_d16_hi v162, v138 offset:33936
	ds_write_b16 v162, v139 offset:34080
	ds_write_b16_d16_hi v162, v139 offset:34224
	ds_write_b16 v162, v140 offset:36096
	ds_write_b16_d16_hi v162, v140 offset:36240
	ds_write_b16 v162, v141 offset:36384
	ds_write_b16_d16_hi v162, v141 offset:36528
	s_cbranch_vccnz .LBB0_711
	s_waitcnt lgkmcnt(0)
	s_barrier
	ds_read_b128 v[2:5], v196
	ds_read_b128 v[6:9], v196 offset:8448
	ds_read_b128 v[10:13], v196 offset:64
	ds_read_b128 v[18:21], v196 offset:128
	ds_read_b128 v[14:17], v196 offset:8512
	ds_read_b128 v[22:25], v196 offset:8640
	s_waitcnt lgkmcnt(5)
	v_mfma_f32_16x16x32_bf16 v[2:5], v[2:5], v[134:137], 0
	s_min_u32 s7, s37, 0x7b
	s_add_i32 s7, s7, 4
	s_lshl_b32 s11, s7, 6
	s_waitcnt lgkmcnt(4)
	v_mfma_f32_16x16x32_bf16 v[6:9], v[6:9], v[134:137], 0
	s_add_i32 s11, s11, s6
	s_mul_hi_i32 s13, s11, 0x6080
	s_mulk_i32 s11, 0x6080
	s_waitcnt lgkmcnt(3)
	v_mfma_f32_16x16x32_bf16 v[2:5], v[10:13], v[126:129], v[2:5]
	ds_read_b128 v[10:13], v196 offset:8576
	s_add_u32 s12, s56, s11
	s_addc_u32 s13, s57, s13
	s_waitcnt lgkmcnt(2)
	v_mfma_f32_16x16x32_bf16 v[6:9], v[14:17], v[126:129], v[6:9]
	ds_read_b128 v[14:17], v196 offset:192
	v_lshl_add_u64 v[126:127], v[0:1], 1, s[12:13]
	s_add_i32 s7, s7, s36
	v_mfma_f32_16x16x32_bf16 v[18:21], v[18:21], v[130:133], v[2:5]
	s_lshl_b32 s7, s7, 3
	s_add_i32 s14, s7, s35
	s_ashr_i32 s15, s14, 31
	s_waitcnt lgkmcnt(1)
	v_mfma_f32_16x16x32_bf16 v[10:13], v[10:13], v[130:133], v[6:9]
	s_lshl_b64 s[14:15], s[14:15], 13
	s_nop 1
	v_add_co_u32_e32 v6, vcc, s18, v126
	s_waitcnt lgkmcnt(0)
	v_mfma_f32_16x16x32_bf16 v[14:17], v[14:17], v[118:121], v[18:21]
	v_addc_co_u32_e32 v7, vcc, 0, v127, vcc
	global_load_dwordx4 v[2:5], v[126:127], off
	s_nop 0
	global_load_dwordx4 v[6:9], v[6:7], off offset:256
	ds_read_b128 v[18:21], v196 offset:256
	ds_read_b128 v[30:33], v196 offset:320
	v_add_co_u32_e32 v34, vcc, s19, v126
	ds_read_b128 v[26:29], v196 offset:8704
	s_nop 0
	v_addc_co_u32_e32 v35, vcc, 0, v127, vcc
	v_add_co_u32_e32 v36, vcc, s20, v126
	v_mfma_f32_16x16x32_bf16 v[22:25], v[22:25], v[118:121], v[10:13]
	s_nop 0
	v_addc_co_u32_e32 v37, vcc, 0, v127, vcc
	v_add_co_u32_e32 v42, vcc, s21, v126
	s_waitcnt lgkmcnt(2)
	v_mfma_f32_16x16x32_bf16 v[18:21], v[18:21], v[122:125], v[14:17]
	global_load_dwordx4 v[10:13], v[34:35], off offset:512
	s_nop 1
	global_load_dwordx4 v[14:17], v[36:37], off offset:768
	ds_read_b128 v[34:37], v196 offset:8768
	v_addc_co_u32_e32 v43, vcc, 0, v127, vcc
	s_waitcnt lgkmcnt(1)
	v_mfma_f32_16x16x32_bf16 v[22:25], v[26:29], v[122:125], v[22:25]
	v_add_co_u32_e32 v44, vcc, s22, v126
	ds_read_b128 v[38:41], v196 offset:8832
	v_mfma_f32_16x16x32_bf16 v[26:29], v[30:33], v[110:113], v[18:21]
	ds_read_b128 v[30:33], v196 offset:384
	v_addc_co_u32_e32 v45, vcc, 0, v127, vcc
	s_waitcnt lgkmcnt(2)
	v_mfma_f32_16x16x32_bf16 v[34:37], v[34:37], v[110:113], v[22:25]
	global_load_dwordx4 v[18:21], v[42:43], off offset:1024
	s_nop 1
	global_load_dwordx4 v[22:25], v[44:45], off offset:1280
	ds_read_b128 v[42:45], v196 offset:448
	ds_read_b128 v[46:49], v196 offset:8896
	s_waitcnt lgkmcnt(2)
	v_mfma_f32_16x16x32_bf16 v[26:29], v[30:33], v[114:117], v[26:29]
	v_add_co_u32_e32 v30, vcc, s23, v126
	s_waitcnt vmcnt(20)
	v_lshlrev_b32_e32 v118, 16, v94
	v_addc_co_u32_e32 v31, vcc, 0, v127, vcc
	v_add_co_u32_e32 v32, vcc, s24, v126
	v_mfma_f32_16x16x32_bf16 v[34:37], v[38:41], v[114:117], v[34:37]
	s_nop 0
	v_addc_co_u32_e32 v33, vcc, 0, v127, vcc
	ds_read_b128 v[38:41], v197 offset:33792
	s_waitcnt lgkmcnt(2)
	v_mfma_f32_16x16x32_bf16 v[42:45], v[42:45], v[106:109], v[26:29]
	s_nop 2
	global_load_dwordx4 v[26:29], v[30:31], off offset:1536
	s_nop 0
	global_load_dwordx4 v[30:33], v[32:33], off offset:1792
	ds_read_b128 v[110:113], v197 offset:36096
	v_and_b32_e32 v94, 0xffff0000, v94
	s_waitcnt lgkmcnt(2)
	v_mfma_f32_16x16x32_bf16 v[46:49], v[46:49], v[106:109], v[34:37]
	ds_read_b128 v[106:109], v197 offset:33856
	v_lshl_add_u64 v[114:115], v[154:155], 0, s[14:15]
	s_waitcnt lgkmcnt(2)
	v_mfma_f32_16x16x32_bf16 v[42:45], v[38:41], v[102:105], v[42:45]
	global_load_dwordx4 v[34:37], v[114:115], off
	global_load_dwordx4 v[38:41], v[114:115], off offset:1024
	ds_read_b128 v[114:117], v197 offset:36160
	s_waitcnt lgkmcnt(2)
	v_mfma_f32_16x16x32_bf16 v[102:105], v[110:113], v[102:105], v[46:49]
	v_lshl_add_u64 v[110:111], v[148:149], 1, s[12:13]
	s_nop 1
	v_mul_f32_e32 v46, 0xbfb8aa3b, v118
	v_mul_f32_e32 v47, 0xbfb8aa3b, v94
	v_exp_f32_e32 v46, v46
	v_exp_f32_e32 v47, v47
	v_lshl_add_u64 v[48:49], v[150:151], 1, s[12:13]
	s_waitcnt lgkmcnt(1)
	v_mfma_f32_16x16x32_bf16 v[106:109], v[106:109], v[98:101], v[42:45]
	v_add_f32_e64 v112, v46, 1.0
	v_add_f32_e64 v113, v47, 1.0
	s_waitcnt lgkmcnt(0)
	v_mfma_f32_16x16x32_bf16 v[98:101], v[114:117], v[98:101], v[102:105]
	global_load_dwordx4 v[42:45], v[48:49], off
	s_nop 0
	global_load_dwordx4 v[46:49], v[110:111], off
	v_and_b32_e32 v111, 0xffff0000, v95
	v_rcp_f32_e32 v102, v113
	s_nop 0
	v_mul_f32_e32 v103, v94, v102
	v_lshlrev_b32_e32 v113, 16, v95
	v_mul_f32_e32 v94, 0xbfb8aa3b, v113
	v_mul_f32_e32 v95, 0xbfb8aa3b, v111
	v_exp_f32_e32 v94, v94
	v_exp_f32_e32 v95, v95
	v_rcp_f32_e32 v102, v112
	s_nop 0
	v_mul_f32_e32 v102, v118, v102
	v_pk_add_f32 v[94:95], v[94:95], 1.0 op_sel_hi:[1,0]
	v_pk_mul_f32 v[102:103], v[102:103], v[106:107]
	v_cvt_pk_bf16_f32 v102, v102, v103
	v_and_b32_e32 v117, 0xffff0000, v97
	v_lshlrev_b32_e32 v110, 16, v96
	v_and_b32_e32 v96, 0xffff0000, v96
	v_mul_f32_e32 v104, 0xbfb8aa3b, v110
	v_mul_f32_e32 v105, 0xbfb8aa3b, v96
	v_exp_f32_e32 v104, v104
	v_exp_f32_e32 v105, v105
	v_rcp_f32_e32 v103, v95
	s_nop 0
	v_mul_f32_e32 v95, v111, v103
	v_pk_add_f32 v[104:105], v[104:105], 1.0 op_sel_hi:[1,0]
	v_rcp_f32_e32 v103, v94
	s_nop 0
	v_mul_f32_e32 v94, v113, v103
	v_rcp_f32_e32 v111, v105
	s_nop 0
	v_mul_f32_e32 v105, v96, v111
	v_lshlrev_b32_e32 v116, 16, v97
	v_mul_f32_e32 v96, 0xbfb8aa3b, v116
	v_mul_f32_e32 v97, 0xbfb8aa3b, v117
	v_exp_f32_e32 v96, v96
	v_exp_f32_e32 v97, v97
	s_nop 0
	v_pk_add_f32 v[96:97], v[96:97], 1.0 op_sel_hi:[1,0]
	v_rcp_f32_e32 v111, v104
	s_nop 0
	v_mul_f32_e32 v104, v110, v111
	v_pk_mul_f32 v[104:105], v[104:105], v[98:99]
	v_rcp_f32_e32 v110, v97
	s_nop 0
	v_mul_f32_e32 v97, v117, v110
	v_pk_mul_f32 v[94:95], v[94:95], v[108:109]
	v_rcp_f32_e32 v110, v96
	s_nop 0
	v_mul_f32_e32 v96, v116, v110
	v_pk_mul_f32 v[110:111], v[96:97], v[100:101]
	v_mov_b32_e32 v97, v98
	v_mov_b32_e32 v98, v107
	v_mov_b32_e32 v96, v106
	v_pk_mul_f32 v[98:99], v[98:99], v[98:99]
	v_cvt_pk_bf16_f32 v103, v94, v95
	v_pk_fma_f32 v[96:97], v[96:97], v[96:97], v[98:99]
	v_mov_b32_e32 v99, v100
	v_mov_b32_e32 v100, v109
	v_mov_b32_e32 v98, v108
	v_pk_mul_f32 v[100:101], v[100:101], v[100:101]
	v_cvt_pk_bf16_f32 v104, v104, v105
	v_pk_fma_f32 v[98:99], v[98:99], v[98:99], v[100:101]
	v_cvt_pk_bf16_f32 v105, v110, v111
	v_pk_add_f32 v[96:97], v[96:97], v[98:99]
	ds_bpermute_b32 v98, v198, v96
	ds_bpermute_b32 v99, v198, v97
	s_waitcnt lgkmcnt(0)
	v_pk_add_f32 v[94:95], v[96:97], v[98:99]
	ds_bpermute_b32 v96, v200, v94
	ds_bpermute_b32 v97, v200, v95
	v_mad_i64_i32 v[98:99], s[12:13], s10, v194, v[152:153]
	global_store_dwordx4 v[98:99], v[102:105], off
	s_and_saveexec_b64 s[12:13], s[4:5]
	s_cbranch_execz .LBB0_710
	s_ashr_i32 s11, s10, 31
	s_lshl_b64 s[14:15], s[10:11], 10
	v_lshl_add_u64 v[98:99], v[156:157], 0, s[14:15]
	s_waitcnt lgkmcnt(0)
	v_pk_add_f32 v[94:95], v[94:95], v[96:97]
	global_store_dwordx2 v[98:99], v[94:95], off
	s_branch .LBB0_710
